# P7 epilogue: row statistics (ss) staged into spare LDS by LDS-DMA during the first K-iteration, read back with ds_read_b128 instead of exposed global loads
# speedup vs baseline: 1.0007x; 1.0005x over previous
;     DI bool next(int i, Unit& u) const { if (!s.next(i >> 1, u)) return false; u.sel = i & 1; return true; }
; template <class Epi, class Sched, bool ALIGN_EPI, bool CONVA>
; DI void gemm_phase(LAS unsigned char* lds, const Gemm g, const Sched& S, const Epi& E) {
;     ...
;         const bool has_next = S.next(ui + 1, nxt);
;         const char* nA = has_next ? (const char*)(nxt.sel ? g.A2 : g.A) + (size_t)nxt.pm * tstepA + abias : cA;
;         const char* nB = has_next ? (const char*)(nxt.sel ? g.Bt2 : g.Bt) + (size_t)nxt.pn * tstepB : cB;
;     DI void operator()(f32x4 (&acc)[2][2][4][2], const Unit& u, int wr, int wc, int fr, int fq) const {
;     ...
;         for (int idx = 0; idx < 8; ++idx) { const int t = t0 + idx; const int tc = t < 0 ? 0 : (t >= MTOK ? MTOK - 1 : t); P8[idx] = *(const f32x4*)(ss + (size_t)tc * 16 + 4 * fq); }
.LBB0_640:
	s_ashr_i32 s95, s94, 31
	s_lshl_b64 s[26:27], s[94:95], 19
	v_readlane_b32 s16, v252, 20
	v_readlane_b32 s17, v252, 21
	s_add_u32 s78, s16, s26
	s_addc_u32 s79, s17, s27
	s_and_b64 s[20:21], s[20:21], exec
	s_cselect_b32 s29, s79, s25
	s_cselect_b32 s30, s78, s24
	s_add_u32 s31, s24, 0x100
	s_addc_u32 s34, s25, 0
	s_mov_b32 s35, -2
	ds_read_b128 v[128:131], v219
	ds_read_b128 v[132:135], v219 offset:1024
	ds_read_b128 v[136:139], v219 offset:2048
	ds_read_b128 v[140:143], v219 offset:3072
	ds_read_b128 v[144:147], v220
	ds_read_b128 v[148:151], v220 offset:1024
	ds_read_b128 v[152:155], v220 offset:2048
	ds_read_b128 v[178:181], v220 offset:3072
	s_add_u32 s20, s22, 0x100
	s_addc_u32 s21, s23, 0
	s_cmp_eq_u32 s35, 12
	s_cselect_b32 s27, s97, s21
	s_cselect_b32 s26, s96, s20
	s_cselect_b32 s25, s29, s34
	s_cselect_b32 s24, s30, s31
	v_lshl_add_u64 v[210:211], s[22:23], 0, v[168:169]
	s_add_i32 m0, s60, 0xc000
	ds_read_b128 v[182:185], v221
	ds_read_b128 v[186:189], v221 offset:1024
	ds_read_b128 v[190:193], v221 offset:2048
	ds_read_b128 v[194:197], v221 offset:3072
	ds_read_b128 v[198:201], v221 offset:4096
	ds_read_b128 v[202:205], v221 offset:5120
	ds_read_b128 v[206:209], v221 offset:6144
	ds_read_b128 v[226:229], v221 offset:7168
	global_load_lds_dwordx4 v[210:211], off
	v_lshl_add_u64 v[210:211], s[22:23], 0, v[170:171]
	s_add_i32 m0, s60, 0xe000
	s_nop 0
	global_load_lds_dwordx4 v[210:211], off
	s_waitcnt vmcnt(8)
	s_waitcnt lgkmcnt(0)
	s_barrier
	s_setprio 1
	s_waitcnt lgkmcnt(0)
	v_mfma_f32_16x16x32_bf16 v[124:127], v[128:131], v[182:185], 0
	v_mfma_f32_16x16x32_bf16 v[116:119], v[136:139], v[182:185], 0
	v_mfma_f32_16x16x32_bf16 v[100:103], v[128:131], v[190:193], 0
	v_mfma_f32_16x16x32_bf16 v[44:47], v[136:139], v[190:193], 0
	v_mfma_f32_16x16x32_bf16 v[92:95], v[128:131], v[198:201], 0
	v_mfma_f32_16x16x32_bf16 v[36:39], v[136:139], v[198:201], 0
	v_mfma_f32_16x16x32_bf16 v[96:99], v[128:131], v[206:209], 0
	v_mfma_f32_16x16x32_bf16 v[40:43], v[136:139], v[206:209], 0
	v_mfma_f32_16x16x32_bf16 v[124:127], v[132:135], v[186:189], v[124:127]
	v_mfma_f32_16x16x32_bf16 v[116:119], v[140:143], v[186:189], v[116:119]
	v_mfma_f32_16x16x32_bf16 v[100:103], v[132:135], v[194:197], v[100:103]
	v_mfma_f32_16x16x32_bf16 v[44:47], v[140:143], v[194:197], v[44:47]
	v_mfma_f32_16x16x32_bf16 v[92:95], v[132:135], v[202:205], v[92:95]
	v_mfma_f32_16x16x32_bf16 v[36:39], v[140:143], v[202:205], v[36:39]
	v_mfma_f32_16x16x32_bf16 v[96:99], v[132:135], v[226:229], v[96:99]
	v_mfma_f32_16x16x32_bf16 v[40:43], v[140:143], v[226:229], v[40:43]
	s_setprio 0
	s_setprio 1
	v_mfma_f32_16x16x32_bf16 v[120:123], v[144:147], v[182:185], 0
	v_mfma_f32_16x16x32_bf16 v[76:79], v[152:155], v[182:185], 0
	v_mfma_f32_16x16x32_bf16 v[88:91], v[144:147], v[190:193], 0
	v_mfma_f32_16x16x32_bf16 v[32:35], v[152:155], v[190:193], 0
	v_mfma_f32_16x16x32_bf16 v[68:71], v[144:147], v[198:201], 0
	v_mfma_f32_16x16x32_bf16 v[20:23], v[152:155], v[198:201], 0
	v_mfma_f32_16x16x32_bf16 v[84:87], v[144:147], v[206:209], 0
	v_mfma_f32_16x16x32_bf16 v[28:31], v[152:155], v[206:209], 0
	v_mfma_f32_16x16x32_bf16 v[120:123], v[148:151], v[186:189], v[120:123]
	v_mfma_f32_16x16x32_bf16 v[76:79], v[178:181], v[186:189], v[76:79]
	v_mfma_f32_16x16x32_bf16 v[88:91], v[148:151], v[194:197], v[88:91]
	v_mfma_f32_16x16x32_bf16 v[32:35], v[178:181], v[194:197], v[32:35]
	v_mfma_f32_16x16x32_bf16 v[68:71], v[148:151], v[202:205], v[68:71]
	v_mfma_f32_16x16x32_bf16 v[20:23], v[178:181], v[202:205], v[20:23]
	v_mfma_f32_16x16x32_bf16 v[84:87], v[148:151], v[226:229], v[84:87]
	v_mfma_f32_16x16x32_bf16 v[28:31], v[178:181], v[226:229], v[28:31]
	s_setprio 0
	s_barrier
	s_add_i32 s22, s13, s81
	v_lshl_add_u64 v[210:211], s[24:25], 0, v[158:159]
	s_mov_b32 m0, s22
	ds_read_b128 v[182:185], v221 offset:16384
	ds_read_b128 v[186:189], v221 offset:17408
	ds_read_b128 v[190:193], v221 offset:18432
	ds_read_b128 v[194:197], v221 offset:19456
	ds_read_b128 v[198:201], v221 offset:20480
	ds_read_b128 v[202:205], v221 offset:21504
	ds_read_b128 v[206:209], v221 offset:22528
	ds_read_b128 v[226:229], v221 offset:23552
	global_load_lds_dwordx4 v[210:211], off
	s_add_i32 m0, s22, 0x2000
	s_add_u32 s22, s24, 0x40000
	v_lshl_add_u64 v[230:231], s[24:25], 0, v[162:163]
	s_addc_u32 s23, s25, 0
	s_add_i32 s36, s62, s81
	global_load_lds_dwordx4 v[230:231], off
	v_lshl_add_u64 v[232:233], s[22:23], 0, v[158:159]
	s_mov_b32 m0, s36
	v_lshl_add_u64 v[234:235], s[26:27], 0, v[160:161]
	global_load_lds_dwordx4 v[232:233], off
	v_lshl_add_u64 v[232:233], s[22:23], 0, v[162:163]
	s_add_i32 m0, s36, 0x2000
	s_nop 0
	global_load_lds_dwordx4 v[232:233], off
	v_lshl_add_u64 v[232:233], s[26:27], 0, v[156:157]
	s_mov_b32 m0, s60
	s_nop 0
	global_load_lds_dwordx4 v[232:233], off
	s_mov_b32 m0, s61
	s_nop 0
	global_load_lds_dwordx4 v[234:235], off
	v_lshlrev_b32_e32 v248, 4, v222
	v_lshrrev_b32_e32 v249, 5, v222
	v_lshlrev_b32_e32 v249, 4, v249
	v_xor_b32_e32 v248, v248, v249
	v_and_b32_e32 v249, 48, v222
	v_mov_b32_e32 v250, s28
	v_mul_u32_u24_e32 v250, 0x3f80, v250
	v_lshl_add_u32 v250, s60, 1, v250
	v_sub_u32_e32 v250, v250, v249
	v_add_u32_e32 v250, 0xffffffc0, v250
	v_xor_b32_e32 v249, 32, v248
	v_add_u32_e32 v248, v250, v248
	v_add_u32_e32 v250, v250, v249
	v_ashrrev_i32_e32 v249, 31, v248
	v_ashrrev_i32_e32 v251, 31, v250
	v_lshl_add_u64 v[248:249], v[166:167], 0, v[248:249]
	v_lshl_add_u64 v[250:251], v[166:167], 0, v[250:251]
	s_lshl_b32 m0, s60, 1
	s_add_i32 m0, m0, 0x20800
	s_nop 0
	global_load_lds_dwordx4 v[248:249], off
	global_load_lds_dwordx4 v[250:251], off offset:1024
	s_waitcnt vmcnt(8)
	s_waitcnt lgkmcnt(0)
	s_barrier
	s_setprio 1
	s_waitcnt lgkmcnt(0)
	v_mfma_f32_16x16x32_bf16 v[64:67], v[128:131], v[182:185], 0
	v_mfma_f32_16x16x32_bf16 v[16:19], v[136:139], v[182:185], 0
	v_mfma_f32_16x16x32_bf16 v[80:83], v[128:131], v[190:193], 0
	v_mfma_f32_16x16x32_bf16 v[24:27], v[136:139], v[190:193], 0
	v_mfma_f32_16x16x32_bf16 v[60:63], v[128:131], v[198:201], 0
	v_mfma_f32_16x16x32_bf16 v[12:15], v[136:139], v[198:201], 0
	v_mfma_f32_16x16x32_bf16 v[112:115], v[128:131], v[206:209], 0
	v_mfma_f32_16x16x32_bf16 v[108:111], v[136:139], v[206:209], 0
	v_mfma_f32_16x16x32_bf16 v[64:67], v[132:135], v[186:189], v[64:67]
	v_mfma_f32_16x16x32_bf16 v[16:19], v[140:143], v[186:189], v[16:19]
	v_mfma_f32_16x16x32_bf16 v[80:83], v[132:135], v[194:197], v[80:83]
	v_mfma_f32_16x16x32_bf16 v[24:27], v[140:143], v[194:197], v[24:27]
	v_mfma_f32_16x16x32_bf16 v[60:63], v[132:135], v[202:205], v[60:63]
	v_mfma_f32_16x16x32_bf16 v[12:15], v[140:143], v[202:205], v[12:15]
	v_mfma_f32_16x16x32_bf16 v[112:115], v[132:135], v[226:229], v[112:115]
	v_mfma_f32_16x16x32_bf16 v[108:111], v[140:143], v[226:229], v[108:111]
	s_setprio 0
	s_setprio 1
	v_mfma_f32_16x16x32_bf16 v[52:55], v[144:147], v[182:185], 0
	v_mfma_f32_16x16x32_bf16 v[4:7], v[152:155], v[182:185], 0
	v_mfma_f32_16x16x32_bf16 v[56:59], v[144:147], v[190:193], 0
	v_mfma_f32_16x16x32_bf16 v[8:11], v[152:155], v[190:193], 0
	v_mfma_f32_16x16x32_bf16 v[48:51], v[144:147], v[198:201], 0
	v_mfma_f32_16x16x32_bf16 v[0:3], v[152:155], v[198:201], 0
	v_mfma_f32_16x16x32_bf16 v[104:107], v[144:147], v[206:209], 0
	v_mfma_f32_16x16x32_bf16 v[72:75], v[152:155], v[206:209], 0
	v_mfma_f32_16x16x32_bf16 v[52:55], v[148:151], v[186:189], v[52:55]
	v_mfma_f32_16x16x32_bf16 v[4:7], v[178:181], v[186:189], v[4:7]
	v_mfma_f32_16x16x32_bf16 v[56:59], v[148:151], v[194:197], v[56:59]
	v_mfma_f32_16x16x32_bf16 v[8:11], v[178:181], v[194:197], v[8:11]
	v_mfma_f32_16x16x32_bf16 v[48:51], v[148:151], v[202:205], v[48:51]
	v_mfma_f32_16x16x32_bf16 v[0:3], v[178:181], v[202:205], v[0:3]
	v_mfma_f32_16x16x32_bf16 v[104:107], v[148:151], v[226:229], v[104:107]
	v_mfma_f32_16x16x32_bf16 v[72:75], v[178:181], v[226:229], v[72:75]
	s_setprio 0
	s_barrier
	s_add_i32 s36, 0, 0x18000
	s_add_i32 s37, 0, 0x1c000
	v_add_u32_e32 v140, s36, v214
	v_add_u32_e32 v164, s37, v214
	ds_read_b128 v[128:131], v140
	ds_read_b128 v[132:135], v140 offset:1024
	ds_read_b128 v[136:139], v140 offset:2048
	ds_read_b128 v[140:143], v140 offset:3072
	ds_read_b128 v[144:147], v164
	ds_read_b128 v[148:151], v164 offset:1024
	ds_read_b128 v[152:155], v164 offset:2048
	ds_read_b128 v[178:181], v164 offset:3072
	s_add_u32 s22, s26, 0x2000
	s_addc_u32 s23, s27, 0
	s_mov_b32 m0, s33
	v_lshl_add_u64 v[236:237], s[22:23], 0, v[156:157]
	ds_read_b128 v[182:185], v221 offset:32768
	ds_read_b128 v[186:189], v221 offset:33792
	ds_read_b128 v[190:193], v221 offset:34816
	ds_read_b128 v[194:197], v221 offset:35840
	ds_read_b128 v[198:201], v221 offset:36864
	ds_read_b128 v[202:205], v221 offset:37888
	ds_read_b128 v[206:209], v221 offset:38912
	ds_read_b128 v[226:229], v221 offset:39936
	global_load_lds_dwordx4 v[236:237], off
	v_lshl_add_u64 v[236:237], s[22:23], 0, v[160:161]
	s_mov_b32 m0, s77
	s_nop 0
	global_load_lds_dwordx4 v[236:237], off
	s_waitcnt vmcnt(8)
	s_waitcnt lgkmcnt(0)
	s_barrier
	s_setprio 1
	s_waitcnt lgkmcnt(0)
	v_mfma_f32_16x16x32_bf16 v[124:127], v[128:131], v[182:185], v[124:127]
	v_mfma_f32_16x16x32_bf16 v[116:119], v[136:139], v[182:185], v[116:119]
	v_mfma_f32_16x16x32_bf16 v[100:103], v[128:131], v[190:193], v[100:103]
	v_mfma_f32_16x16x32_bf16 v[44:47], v[136:139], v[190:193], v[44:47]
	v_mfma_f32_16x16x32_bf16 v[92:95], v[128:131], v[198:201], v[92:95]
	v_mfma_f32_16x16x32_bf16 v[36:39], v[136:139], v[198:201], v[36:39]
	v_mfma_f32_16x16x32_bf16 v[96:99], v[128:131], v[206:209], v[96:99]
	v_mfma_f32_16x16x32_bf16 v[40:43], v[136:139], v[206:209], v[40:43]
	v_mfma_f32_16x16x32_bf16 v[124:127], v[132:135], v[186:189], v[124:127]
	v_mfma_f32_16x16x32_bf16 v[116:119], v[140:143], v[186:189], v[116:119]
	v_mfma_f32_16x16x32_bf16 v[100:103], v[132:135], v[194:197], v[100:103]
	v_mfma_f32_16x16x32_bf16 v[44:47], v[140:143], v[194:197], v[44:47]
	v_mfma_f32_16x16x32_bf16 v[92:95], v[132:135], v[202:205], v[92:95]
	v_mfma_f32_16x16x32_bf16 v[36:39], v[140:143], v[202:205], v[36:39]
	v_mfma_f32_16x16x32_bf16 v[96:99], v[132:135], v[226:229], v[96:99]
	v_mfma_f32_16x16x32_bf16 v[40:43], v[140:143], v[226:229], v[40:43]
	s_setprio 0
	s_setprio 1
	v_mfma_f32_16x16x32_bf16 v[120:123], v[144:147], v[182:185], v[120:123]
	v_mfma_f32_16x16x32_bf16 v[76:79], v[152:155], v[182:185], v[76:79]
	v_mfma_f32_16x16x32_bf16 v[88:91], v[144:147], v[190:193], v[88:91]
	v_mfma_f32_16x16x32_bf16 v[32:35], v[152:155], v[190:193], v[32:35]
	v_mfma_f32_16x16x32_bf16 v[68:71], v[144:147], v[198:201], v[68:71]
	v_mfma_f32_16x16x32_bf16 v[20:23], v[152:155], v[198:201], v[20:23]
	v_mfma_f32_16x16x32_bf16 v[84:87], v[144:147], v[206:209], v[84:87]
	v_mfma_f32_16x16x32_bf16 v[28:31], v[152:155], v[206:209], v[28:31]
	v_mfma_f32_16x16x32_bf16 v[120:123], v[148:151], v[186:189], v[120:123]
	v_mfma_f32_16x16x32_bf16 v[76:79], v[178:181], v[186:189], v[76:79]
	v_mfma_f32_16x16x32_bf16 v[88:91], v[148:151], v[194:197], v[88:91]
	v_mfma_f32_16x16x32_bf16 v[32:35], v[178:181], v[194:197], v[32:35]
	v_mfma_f32_16x16x32_bf16 v[68:71], v[148:151], v[202:205], v[68:71]
	v_mfma_f32_16x16x32_bf16 v[20:23], v[178:181], v[202:205], v[20:23]
	v_mfma_f32_16x16x32_bf16 v[84:87], v[148:151], v[226:229], v[84:87]
	v_mfma_f32_16x16x32_bf16 v[28:31], v[178:181], v[226:229], v[28:31]
	s_setprio 0
	s_barrier
; #define PG8_WAIT_V(n) asm volatile("s_waitcnt vmcnt(" #n ")" ::: "memory")
; template <class Epi, class Sched, bool ALIGN_EPI, bool CONVA>
; DI void gemm_phase(LAS unsigned char* lds, const Gemm g, const Sched& S, const Epi& E) {
;     ...
;         for (int t = 0; t < nt; t += 2) {
;             const bool last = (t == nt - 2);
;             const char* a1 = cA + (size_t)(t + 1) * kstep;
;             const char* a2 = last ? nA : cA + (size_t)(t + 2) * kstep; const char* b2 = last ? nB : cB + (size_t)(t + 2) * kstep;
;             const char* a3 = a2 + kstep; const char* b3 = b2 + kstep;
;             PG8_KBODY(PG8_WAIT_V(8));
	s_add_i32 s22, s36, s81
	v_lshl_add_u64 v[210:211], v[210:211], 0, s[84:85]
	s_mov_b32 m0, s22
	ds_read_b128 v[182:185], v221 offset:49152
	ds_read_b128 v[186:189], v221 offset:50176
	ds_read_b128 v[190:193], v221 offset:51200
	ds_read_b128 v[194:197], v221 offset:52224
	ds_read_b128 v[198:201], v221 offset:53248
	ds_read_b128 v[202:205], v221 offset:54272
	ds_read_b128 v[206:209], v221 offset:55296
	ds_read_b128 v[226:229], v221 offset:56320
	global_load_lds_dwordx4 v[210:211], off
	s_add_i32 m0, s22, 0x2000
	s_add_u32 s22, s24, 0x40080
	v_lshl_add_u64 v[210:211], v[230:231], 0, s[84:85]
	s_addc_u32 s23, s25, 0
	s_add_i32 s24, s37, s81
	global_load_lds_dwordx4 v[210:211], off
	v_lshl_add_u64 v[210:211], s[22:23], 0, v[158:159]
	s_mov_b32 m0, s24
	s_nop 0
	global_load_lds_dwordx4 v[210:211], off
	v_lshl_add_u64 v[210:211], s[22:23], 0, v[162:163]
	s_add_i32 m0, s24, 0x2000
	s_nop 0
	global_load_lds_dwordx4 v[210:211], off
	v_lshl_add_u64 v[210:211], v[232:233], 0, s[84:85]
	s_mov_b32 m0, s67
	s_nop 0
	global_load_lds_dwordx4 v[210:211], off
	v_lshl_add_u64 v[210:211], v[234:235], 0, s[84:85]
	s_mov_b32 m0, s10
	s_nop 0
	global_load_lds_dwordx4 v[210:211], off
	s_waitcnt vmcnt(8)
	s_waitcnt lgkmcnt(0)
	s_barrier
	s_setprio 1
	s_waitcnt lgkmcnt(0)
	v_mfma_f32_16x16x32_bf16 v[64:67], v[128:131], v[182:185], v[64:67]
	v_mfma_f32_16x16x32_bf16 v[16:19], v[136:139], v[182:185], v[16:19]
	v_mfma_f32_16x16x32_bf16 v[80:83], v[128:131], v[190:193], v[80:83]
	v_mfma_f32_16x16x32_bf16 v[24:27], v[136:139], v[190:193], v[24:27]
	v_mfma_f32_16x16x32_bf16 v[60:63], v[128:131], v[198:201], v[60:63]
	v_mfma_f32_16x16x32_bf16 v[12:15], v[136:139], v[198:201], v[12:15]
	v_mfma_f32_16x16x32_bf16 v[112:115], v[128:131], v[206:209], v[112:115]
	v_mfma_f32_16x16x32_bf16 v[108:111], v[136:139], v[206:209], v[108:111]
	v_mfma_f32_16x16x32_bf16 v[64:67], v[132:135], v[186:189], v[64:67]
	v_mfma_f32_16x16x32_bf16 v[16:19], v[140:143], v[186:189], v[16:19]
	v_mfma_f32_16x16x32_bf16 v[80:83], v[132:135], v[194:197], v[80:83]
	v_mfma_f32_16x16x32_bf16 v[24:27], v[140:143], v[194:197], v[24:27]
	v_mfma_f32_16x16x32_bf16 v[60:63], v[132:135], v[202:205], v[60:63]
	v_mfma_f32_16x16x32_bf16 v[12:15], v[140:143], v[202:205], v[12:15]
	v_mfma_f32_16x16x32_bf16 v[112:115], v[132:135], v[226:229], v[112:115]
	v_mfma_f32_16x16x32_bf16 v[108:111], v[140:143], v[226:229], v[108:111]
	s_setprio 0
	s_setprio 1
	v_mfma_f32_16x16x32_bf16 v[52:55], v[144:147], v[182:185], v[52:55]
	v_mfma_f32_16x16x32_bf16 v[4:7], v[152:155], v[182:185], v[4:7]
	v_mfma_f32_16x16x32_bf16 v[56:59], v[144:147], v[190:193], v[56:59]
	v_mfma_f32_16x16x32_bf16 v[8:11], v[152:155], v[190:193], v[8:11]
	v_mfma_f32_16x16x32_bf16 v[48:51], v[144:147], v[198:201], v[48:51]
	v_mfma_f32_16x16x32_bf16 v[0:3], v[152:155], v[198:201], v[0:3]
	v_mfma_f32_16x16x32_bf16 v[104:107], v[144:147], v[206:209], v[104:107]
	v_mfma_f32_16x16x32_bf16 v[72:75], v[152:155], v[206:209], v[72:75]
	v_mfma_f32_16x16x32_bf16 v[52:55], v[148:151], v[186:189], v[52:55]
	v_mfma_f32_16x16x32_bf16 v[4:7], v[178:181], v[186:189], v[4:7]
	v_mfma_f32_16x16x32_bf16 v[56:59], v[148:151], v[194:197], v[56:59]
	v_mfma_f32_16x16x32_bf16 v[8:11], v[178:181], v[194:197], v[8:11]
	v_mfma_f32_16x16x32_bf16 v[48:51], v[148:151], v[202:205], v[48:51]
	v_mfma_f32_16x16x32_bf16 v[0:3], v[178:181], v[202:205], v[0:3]
	v_mfma_f32_16x16x32_bf16 v[104:107], v[148:151], v[226:229], v[104:107]
	v_mfma_f32_16x16x32_bf16 v[72:75], v[178:181], v[226:229], v[72:75]
	s_setprio 0
	s_barrier
	s_add_i32 s35, s35, 2
	s_add_u32 s31, s31, 0x100
	s_addc_u32 s34, s34, 0
	s_cmp_gt_u32 s35, 13
	s_mov_b64 s[22:23], s[20:21]

;     DI void operator()(f32x4 (&acc)[2][2][4][2], const Unit& u, int wr, int wc, int fr, int fq) const {
;     ...
;         for (int idx = 0; idx < 8; ++idx) { const int t = t0 + idx; const int tc = t < 0 ? 0 : (t >= MTOK ? MTOK - 1 : t); P8[idx] = *(const f32x4*)(ss + (size_t)tc * 16 + 4 * fq); }
; #pragma unroll
;         for (int idx = 0; idx < 8; ++idx) { const int rho = 128 * wr + 8 * fr + idx, t = t0 + idx;
;             const f32x4 p = P8[idx]; float s = (p[0] + p[1]) + (p[2] + p[3]); s += __shfl_xor(s, 16); s += __shfl_xor(s, 32);
;             const float rs = __builtin_amdgcn_rsqf(s * (1.f / DM) + EPS);
; #pragma unroll
;             for (int bj = 0; bj < 2; ++bj)
; #pragma unroll
;                 for (int n = 0; n < 2; ++n) acc[idx >> 2][bj][idx & 3][n] *= rs;
;             if (seq_start(t)) upz |= 1u << idx;
;             if (t + 1 >= MTOK || seq_start(t + 1)) dnz |= 1u << idx;
.LBB0_644:
	s_mul_i32 s20, s28, 0xfe
	v_and_b32_e32 v248, 3, v222
	v_lshrrev_b32_e32 v249, 4, v222
	v_xor_b32_e32 v248, v248, v249
	v_lshlrev_b32_e32 v248, 4, v248
	v_lshl_add_u32 v248, v215, 6, v248
	v_add_u32_e32 v248, 0x20840, v248
	v_add_u32_e32 v233, s20, v215
	v_add_u32_e32 v232, 1, v233
	ds_read_b128 v[178:181], v248
	ds_read_b128 v[148:151], v248 offset:64
	v_add_u32_e32 v231, 2, v233
	v_add_u32_e32 v230, 3, v233
	v_add_u32_e32 v229, 4, v233
	ds_read_b128 v[152:155], v248 offset:128
	ds_read_b128 v[140:143], v248 offset:192
	v_add_u32_e32 v228, 5, v233
	v_add_u32_e32 v227, 6, v233
	ds_read_b128 v[144:147], v248 offset:256
	ds_read_b128 v[132:135], v248 offset:320
	v_add_u32_e32 v226, 7, v233
	ds_read_b128 v[136:139], v248 offset:384
	ds_read_b128 v[128:131], v248 offset:448
	v_and_b32_e32 v182, 64, v222
	v_xor_b32_e32 v164, 16, v222
	v_add_u32_e32 v184, 64, v182
	v_cmp_lt_i32_e32 vcc, v164, v184
	s_mov_b32 s20, 0x13ffe
	s_mov_b32 s22, 0x13fff
	v_cndmask_b32_e32 v164, v222, v164, vcc
	v_lshlrev_b32_e32 v185, 2, v164
	v_cmp_lt_i32_e64 s[64:65], s20, v233
	v_and_b32_e32 v187, 0xffe, v232
	s_waitcnt lgkmcnt(0)
	v_mov_b32_e32 v182, v179
	v_mov_b32_e32 v183, v180
	v_mov_b32_e32 v179, v181
	v_pk_add_f32 v[178:179], v[182:183], v[178:179]
	s_nop 0
	v_add_f32_e32 v164, v178, v179
	ds_bpermute_b32 v178, v185, v164
	v_xor_b32_e32 v179, 32, v222
	v_cmp_lt_i32_e32 vcc, v179, v184
	s_waitcnt lgkmcnt(0)
	v_add_f32_e32 v181, v164, v178
	v_cndmask_b32_e32 v179, v222, v179, vcc
	v_lshlrev_b32_e32 v186, 2, v179
	ds_bpermute_b32 v184, v186, v181
	v_cmp_gt_i32_e32 vcc, s22, v233
	s_and_saveexec_b64 s[22:23], vcc
	s_xor_b64 s[26:27], exec, s[22:23]
	v_readlane_b32 s95, v252, 34
	s_movk_i32 s22, 0x3ffe
	v_and_b32_e32 v187, 0xffe, v232
	v_cmp_lt_i32_e64 s[22:23], s22, v233
	v_cmp_eq_u32_e64 s[24:25], 0, v187
	v_cmp_eq_u32_e32 vcc, 0, v232
	s_and_b64 s[22:23], s[22:23], s[24:25]
	s_or_b64 s[22:23], vcc, s[22:23]
	v_cndmask_b32_e64 v178, 0, 1, s[22:23]
	s_andn2_saveexec_b64 s[22:23], s[26:27]
	v_mov_b32_e32 v178, 1
	s_or_b64 exec, exec, s[22:23]
	v_mov_b32_e32 v182, v149
	v_mov_b32_e32 v183, v150
	v_mov_b32_e32 v149, v151
	v_pk_add_f32 v[148:149], v[182:183], v[148:149]
	s_mov_b32 s16, 0x13ffd
	v_add_f32_e32 v150, v148, v149
	v_mov_b32_e32 v148, v153
	v_mov_b32_e32 v149, v154
	v_mov_b32_e32 v153, v155
	v_pk_add_f32 v[148:149], v[148:149], v[152:153]
	ds_bpermute_b32 v151, v185, v150
	v_add_f32_e32 v148, v148, v149
	ds_bpermute_b32 v149, v185, v148
	s_mov_b32 s22, 0x13ffc
	v_cmp_lt_i32_e64 s[72:73], s16, v233
	s_waitcnt lgkmcnt(1)
	v_add_f32_e32 v155, v150, v151
	ds_bpermute_b32 v164, v186, v155
	s_waitcnt lgkmcnt(1)
	v_add_f32_e32 v149, v148, v149
	ds_bpermute_b32 v153, v186, v149
	v_cmp_lt_i32_e64 s[86:87], s22, v233
	v_cmp_gt_i32_e32 vcc, s16, v233
	s_mov_b64 s[26:27], 0
	v_and_b32_e32 v150, 0xffe, v230
	s_and_saveexec_b64 s[28:29], vcc
	s_xor_b64 s[30:31], exec, s[28:29]
	s_movk_i32 s26, 0x3ffc
	v_and_b32_e32 v150, 0xffe, v230
	v_cmp_lt_i32_e64 s[26:27], s26, v233
	v_cmp_eq_u32_e64 s[28:29], 0, v150
	v_cmp_eq_u32_e32 vcc, 0, v230
	s_and_b64 s[26:27], s[26:27], s[28:29]
	s_or_b64 s[26:27], vcc, s[26:27]
	s_and_b64 s[26:27], s[26:27], exec
	s_andn2_saveexec_b64 s[28:29], s[30:31]
	s_or_b64 s[26:27], s[26:27], exec
	s_or_b64 exec, exec, s[28:29]
	v_or_b32_e32 v148, 2, v178
	v_cndmask_b32_e64 v148, v178, v148, s[72:73]
	s_and_saveexec_b64 s[28:29], s[26:27]
	v_or_b32_e32 v148, 4, v148
	s_or_b64 exec, exec, s[28:29]
	v_mov_b32_e32 v178, v141
	v_mov_b32_e32 v179, v142
	v_mov_b32_e32 v141, v143
	v_pk_add_f32 v[140:141], v[178:179], v[140:141]
	s_mov_b32 s26, 0x13ffa
	v_add_f32_e32 v142, v140, v141
	v_mov_b32_e32 v140, v145
	v_mov_b32_e32 v141, v146
	v_mov_b32_e32 v145, v147
	v_pk_add_f32 v[140:141], v[140:141], v[144:145]
	ds_bpermute_b32 v143, v185, v142
	v_add_f32_e32 v140, v140, v141
	ds_bpermute_b32 v141, v185, v140
	v_cmp_lt_i32_e64 s[88:89], s69, v233
	v_cmp_lt_i32_e64 s[70:71], s26, v233
	s_waitcnt lgkmcnt(1)
;     DI void operator()(f32x4 (&acc)[2][2][4][2], const Unit& u, int wr, int wc, int fr, int fq) const {
;     ...
;         for (int idx = 0; idx < 8; ++idx) { const int rho = 128 * wr + 8 * fr + idx, t = t0 + idx;
;             const f32x4 p = P8[idx]; float s = (p[0] + p[1]) + (p[2] + p[3]); s += __shfl_xor(s, 16); s += __shfl_xor(s, 32);
;             const float rs = __builtin_amdgcn_rsqf(s * (1.f / DM) + EPS);
; #pragma unroll
;             for (int bj = 0; bj < 2; ++bj)
; #pragma unroll
;                 for (int n = 0; n < 2; ++n) acc[idx >> 2][bj][idx & 3][n] *= rs;
;             if (seq_start(t)) upz |= 1u << idx;
;             if (t + 1 >= MTOK || seq_start(t + 1)) dnz |= 1u << idx;
;             if (rho >= 1 && rho <= 254 && t < MTOK) stm |= 1u << idx; }
;         const bool anyb = __builtin_amdgcn_ballot_w64((upz | dnz) != 0u) != 0ull;
	v_add_f32_e32 v154, v142, v143
	ds_bpermute_b32 v180, v186, v154
	s_waitcnt lgkmcnt(1)
	v_add_f32_e32 v182, v140, v141
	ds_bpermute_b32 v183, v186, v182
	v_cmp_gt_i32_e32 vcc, s69, v233
	s_mov_b64 s[30:31], 0
	v_and_b32_e32 v140, 0xffe, v228
	s_and_saveexec_b64 s[34:35], vcc
	s_xor_b64 s[36:37], exec, s[34:35]
	s_movk_i32 s30, 0x3ffa
	v_and_b32_e32 v140, 0xffe, v228
	v_cmp_lt_i32_e64 s[30:31], s30, v233
	v_cmp_eq_u32_e64 s[34:35], 0, v140
	v_cmp_eq_u32_e32 vcc, 0, v228
	s_and_b64 s[30:31], s[30:31], s[34:35]
	s_or_b64 s[30:31], vcc, s[30:31]
	s_and_b64 s[30:31], s[30:31], exec
	s_andn2_saveexec_b64 s[34:35], s[36:37]
	s_or_b64 s[30:31], s[30:31], exec
	s_or_b64 exec, exec, s[34:35]
	v_or_b32_e32 v141, 8, v148
	v_cndmask_b32_e64 v141, v148, v141, s[88:89]
	s_and_saveexec_b64 s[34:35], s[30:31]
	v_or_b32_e32 v141, 16, v141
	s_or_b64 exec, exec, s[34:35]
	v_mov_b32_e32 v142, v133
	v_mov_b32_e32 v143, v134
	v_mov_b32_e32 v133, v135
	v_pk_add_f32 v[132:133], v[142:143], v[132:133]
	s_mov_b32 s30, 0x13ff8
	v_add_f32_e32 v134, v132, v133
	v_mov_b32_e32 v132, v137
	v_mov_b32_e32 v133, v138
	v_mov_b32_e32 v137, v139
	v_pk_add_f32 v[132:133], v[132:133], v[136:137]
	ds_bpermute_b32 v135, v185, v134
	v_add_f32_e32 v132, v132, v133
	ds_bpermute_b32 v133, v185, v132
	v_cmp_lt_i32_e64 s[34:35], s63, v233
	v_cmp_lt_i32_e64 s[74:75], s30, v233
	s_waitcnt lgkmcnt(1)
	v_add_f32_e32 v148, v134, v135
	ds_bpermute_b32 v179, v186, v148
	s_waitcnt lgkmcnt(1)
	v_add_f32_e32 v152, v132, v133
	ds_bpermute_b32 v178, v186, v152
	v_cmp_gt_i32_e32 vcc, s63, v233
	s_mov_b64 s[36:37], 0
	v_and_b32_e32 v132, 0xffe, v226
	s_and_saveexec_b64 s[38:39], vcc
	s_xor_b64 s[42:43], exec, s[38:39]
	s_movk_i32 s36, 0x3ff8
	v_and_b32_e32 v132, 0xffe, v226
	v_cmp_lt_i32_e64 s[36:37], s36, v233
	v_cmp_eq_u32_e64 s[38:39], 0, v132
	v_cmp_eq_u32_e32 vcc, 0, v226
	s_and_b64 s[36:37], s[36:37], s[38:39]
	s_or_b64 s[36:37], vcc, s[36:37]
	s_and_b64 s[36:37], s[36:37], exec
	s_andn2_saveexec_b64 s[38:39], s[42:43]
	s_or_b64 s[36:37], s[36:37], exec
	s_or_b64 exec, exec, s[38:39]
	v_or_b32_e32 v133, 32, v141
	v_cndmask_b32_e64 v133, v141, v133, s[34:35]
	s_and_saveexec_b64 s[38:39], s[36:37]
	v_or_b32_e32 v133, 64, v133
	s_or_b64 exec, exec, s[38:39]
	s_movk_i32 s36, 0x3ffb
	v_cmp_gt_i32_e64 s[36:37], s36, v233
	v_cmp_ne_u32_e64 s[38:39], 0, v140
	v_cmp_ne_u32_e32 vcc, 0, v228
	s_or_b64 s[36:37], s[36:37], s[38:39]
	s_and_b64 s[48:49], vcc, s[36:37]
	s_movk_i32 s36, 0x3ffd
	v_mov_b32_e32 v134, v129
	v_mov_b32_e32 v135, v130
	v_mov_b32_e32 v129, v131
	v_cmp_gt_i32_e64 s[36:37], s36, v233
	v_cmp_ne_u32_e64 s[38:39], 0, v150
	v_pk_add_f32 v[128:129], v[134:135], v[128:129]
	v_cmp_ne_u32_e32 vcc, 0, v230
	s_or_b64 s[36:37], s[36:37], s[38:39]
	v_add_f32_e32 v128, v128, v129
	s_and_b64 s[42:43], vcc, s[36:37]
	s_movk_i32 s36, 0x3fff
	ds_bpermute_b32 v129, v185, v128
	v_cmp_gt_i32_e64 s[36:37], s36, v233
	v_cmp_ne_u32_e64 s[38:39], 0, v187
	v_cmp_ne_u32_e32 vcc, 0, v232
	s_or_b64 s[36:37], s[36:37], s[38:39]
	s_and_b64 s[44:45], vcc, s[36:37]
	s_movk_i32 s36, 0x3ff9
	v_cmp_gt_i32_e64 s[36:37], s36, v233
	v_cmp_ne_u32_e64 s[38:39], 0, v132
	s_waitcnt lgkmcnt(0)
	v_add_f32_e32 v128, v128, v129
	v_cmp_ne_u32_e32 vcc, 0, v226
	s_or_b64 s[36:37], s[36:37], s[38:39]
	ds_bpermute_b32 v129, v186, v128
	s_and_b64 s[54:55], vcc, s[36:37]
	s_mov_b32 s36, 0x13ff7
	v_cndmask_b32_e64 v136, 32, 0, s[48:49]
	v_cndmask_b32_e64 v137, 8, 0, s[42:43]
	v_cndmask_b32_e64 v130, 2, 0, s[44:45]
	v_or_b32_e32 v132, 0x80, v133
	v_cmp_lt_i32_e32 vcc, s36, v233
	v_cndmask_b32_e64 v131, v225, 0, s[54:55]
	v_or3_b32 v130, v137, v130, v136
	v_cndmask_b32_e32 v234, v133, v132, vcc
	v_readlane_b32 s16, v252, 0
	v_or3_b32 v130, v130, v131, v234
	v_readlane_b32 s17, v252, 1
	v_cmp_ne_u32_e64 s[36:37], 0, v130
	s_and_b64 vcc, exec, s[16:17]
	s_cbranch_vccz .LBB0_668
	v_readlane_b32 s16, v252, 46
	v_readlane_b32 s17, v252, 47
	s_mov_b64 s[46:47], 0
	s_and_b64 s[38:39], s[16:17], exec
	s_branch .LBB0_669
